# phase 0: item permutation - odd blocks stream activation rows first and do their weight-transpose tile later (tiles and row streaming no longer in separate windows)
# speedup vs baseline: 1.0127x; 1.0024x over previous
; DEVINL int tidx() { int t = threadIdx.x; asm volatile("" : "+v"(t)); return t; }
; DEVINL int bidx() { int t = blockIdx.x; asm volatile("" : "+s"(t)); return t; }
; DEVINL void s5_param(const Params& p, int idx) {
;   const int g = idx >> 6, n = idx & 63;
;   float lre = fminf(p.a_re[idx], -1e-4f), lim = p.a_im[idx];
;   float dt = expf(p.log_dt[g]);
;   float mag = expf(lre * dt);
;   float ar = mag * cosf(lim * dt), ai = mag * sinf(lim * dt);
; DEVINL void phase0(const Params& p, char* smem) {
;   for (int it = bidx(); it < NTR_A + NXROW_ITEMS + 8; it += gridDim.x) {
;     if (it < NTR_A) {
;       tr_tile(p, smem, 0, it / 16, it % 16);
;     } else if (it < NTR_A + NXROW_ITEMS) {
;       xrow_prep<4>(p, (it - NTR_A) * 16 + (tidx() >> 6) * 4);
;     } else {
;       s5_param(p, (it - NTR_A - NXROW_ITEMS) * 256 + tidx());
.LBB0_1462:
	s_or_b64 exec, exec, s[36:37]
	s_waitcnt vmcnt(0)
	v_subrev_u32_e32 v197, 0x400, v1
	v_cmp_gt_u32_e32 vcc, 0x200, v1
	s_mov_b64 s[0:1], vcc
	v_mov_b32_e32 v198, 0x400
	v_mov_b32_e32 v199, 0xfffffc00
	v_cndmask_b32_e32 v198, v199, v198, vcc
	v_cndmask_b32_e32 v196, v197, v1, vcc
	v_cmp_gt_u32_e32 vcc, 0x200, v197
	s_or_b64 s[0:1], s[0:1], vcc
	v_and_b32_e32 v199, 1, v196
	v_cmp_eq_u32_e32 vcc, 1, v199
	s_and_b64 s[0:1], s[0:1], vcc
	v_subrev_u32_e32 v199, 0x70, v196
	v_cmp_le_u32_e32 vcc, 8, v199
	s_and_b64 vcc, s[0:1], vcc
	v_add_u32_e32 v198, v1, v198
	s_nop 0
	v_cndmask_b32_e32 v1, v1, v198, vcc
	v_subrev_u32_e32 v196, 0x70, v1
	v_add_u32_e32 v197, 0x5f8, v1
	v_cmp_gt_u32_e32 vcc, 8, v196
	v_subrev_u32_e32 v196, 0x668, v1
	s_nop 0
	v_cndmask_b32_e32 v197, v1, v197, vcc
	v_cmp_gt_u32_e32 vcc, 8, v196
	v_subrev_u32_e32 v196, 0x5f8, v1
	s_nop 0
	v_cndmask_b32_e32 v1, v197, v196, vcc
	v_add_u32_e32 v1, v1, v104
	s_movk_i32 s0, 0x66f
	v_cmp_lt_i32_e32 vcc, s0, v1
	s_or_b64 s[40:41], vcc, s[40:41]
	s_andn2_b64 exec, exec, s[40:41]
	s_cbranch_execz .LBB0_1545
.LBB0_1463:
	v_subrev_u32_e32 v196, 0x70, v1
	v_add_u32_e32 v197, 0x5f8, v1
	v_cmp_gt_u32_e32 vcc, 8, v196
	v_subrev_u32_e32 v196, 0x668, v1
	s_nop 0
	v_cndmask_b32_e32 v197, v1, v197, vcc
	v_cmp_gt_u32_e32 vcc, 8, v196
	v_subrev_u32_e32 v196, 0x5f8, v1
	s_nop 0
	v_cndmask_b32_e32 v1, v197, v196, vcc
	v_subrev_u32_e32 v197, 0x400, v1
	v_cmp_gt_u32_e32 vcc, 0x200, v1
	s_mov_b64 s[0:1], vcc
	v_mov_b32_e32 v198, 0x400
	v_mov_b32_e32 v199, 0xfffffc00
	v_cndmask_b32_e32 v198, v199, v198, vcc
	v_cndmask_b32_e32 v196, v197, v1, vcc
	v_cmp_gt_u32_e32 vcc, 0x200, v197
	s_or_b64 s[0:1], s[0:1], vcc
	v_and_b32_e32 v199, 1, v196
	v_cmp_eq_u32_e32 vcc, 1, v199
	s_and_b64 s[0:1], s[0:1], vcc
	v_subrev_u32_e32 v199, 0x70, v196
	v_cmp_le_u32_e32 vcc, 8, v199
	s_and_b64 vcc, s[0:1], vcc
	v_add_u32_e32 v198, v1, v198
	s_nop 0
	v_cndmask_b32_e32 v1, v1, v198, vcc
	s_movk_i32 s0, 0x21f
	v_cmp_lt_i32_e32 vcc, s0, v1
	s_and_saveexec_b64 s[0:1], vcc
	s_xor_b64 s[42:43], exec, s[0:1]
	s_cbranch_execz .LBB0_1517
	s_movk_i32 s0, 0x667
	v_cmp_lt_u32_e32 vcc, s0, v1
	s_and_saveexec_b64 s[0:1], vcc
	s_xor_b64 s[44:45], exec, s[0:1]
	s_cbranch_execz .LBB0_1475
	s_waitcnt vmcnt(0) lgkmcnt(0)
	v_lshlrev_b32_e32 v4, 8, v1
	v_mov_b32_e32 v3, v0
	s_mov_b32 s0, 0xfff99800
	s_nop 0
	v_add3_u32 v8, v4, v3, s0
	v_ashrrev_i32_e32 v14, 6, v8
	v_ashrrev_i32_e32 v9, 31, v8
	v_lshlrev_b64 v[6:7], 2, v[8:9]
	v_ashrrev_i32_e32 v15, 31, v14
	s_waitcnt lgkmcnt(0)
	v_lshl_add_u64 v[4:5], s[74:75], 0, v[6:7]
	v_lshl_add_u64 v[10:11], v[14:15], 2, s[8:9]
	global_load_dword v4, v[4:5], off
	v_lshl_add_u64 v[6:7], s[76:77], 0, v[6:7]
	global_load_dword v5, v[10:11], off
	s_mov_b32 s0, 0x3fb8aa3b
	global_load_dword v6, v[6:7], off
	s_waitcnt vmcnt(1)
	v_mul_f32_e32 v7, 0x3fb8aa3b, v5
	v_fma_f32 v10, v5, s0, -v7
	v_rndne_f32_e32 v11, v7
	v_fmac_f32_e32 v10, 0x32a5705f, v5
	v_sub_f32_e32 v7, v7, v11
	v_add_f32_e32 v7, v7, v10
	v_exp_f32_e32 v7, v7
	v_cvt_i32_f32_e32 v10, v11
	s_mov_b32 s0, 0xc2ce8ed0
	v_cmp_ngt_f32_e32 vcc, s0, v5
	s_mov_b32 s0, 0x42b17218
	v_ldexp_f32 v7, v7, v10
	v_cndmask_b32_e32 v7, 0, v7, vcc
	v_cmp_nlt_f32_e32 vcc, s0, v5
	s_brev_b32 s0, 18
	s_nop 0
	v_cndmask_b32_e32 v10, v127, v7, vcc
	s_waitcnt vmcnt(0)
	v_mul_f32_e32 v5, v6, v10
	v_and_b32_e32 v7, 0x7fffffff, v5
	v_cmp_nlt_f32_e64 s[46:47], |v5|, s0
	v_lshrrev_b32_e32 v16, 23, v7
	v_and_b32_e32 v13, 0x7fffff, v7
	s_and_saveexec_b64 s[0:1], s[46:47]
	s_xor_b64 s[66:67], exec, s[0:1]
	s_cbranch_execz .LBB0_1467
	v_add_u32_e32 v11, 0xffffff88, v16
	v_cmp_lt_u32_e32 vcc, 63, v11
	s_mov_b32 s0, 0xfe5163ab
	v_mov_b32_e32 v21, v2
	v_cndmask_b32_e32 v12, 0, v128, vcc
	v_add_u32_e32 v11, v12, v11
	v_cmp_lt_u32_e64 s[34:35], 31, v11
	v_mov_b32_e32 v23, v2
	v_mov_b32_e32 v25, v2
	v_cndmask_b32_e64 v12, 0, v129, s[34:35]
	v_add_u32_e32 v11, v12, v11
	v_cmp_lt_u32_e64 s[36:37], 31, v11
	v_mov_b32_e32 v27, v2
	v_mov_b32_e32 v29, v2
	v_cndmask_b32_e64 v12, 0, v129, s[36:37]
	v_add_u32_e32 v11, v12, v11
	v_or_b32_e32 v12, 0x800000, v13
	v_mad_u64_u32 v[18:19], s[0:1], v12, s0, 0
	v_mov_b32_e32 v20, v19
	s_mov_b32 s0, 0x3c439041
	v_mad_u64_u32 v[20:21], s[0:1], v12, s0, v[20:21]
	v_mov_b32_e32 v22, v21
	s_mov_b32 s0, 0xdb629599
	v_mad_u64_u32 v[22:23], s[0:1], v12, s0, v[22:23]
	v_mov_b32_e32 v24, v23
	s_mov_b32 s0, 0xf534ddc0
	v_mad_u64_u32 v[24:25], s[0:1], v12, s0, v[24:25]
	v_mov_b32_e32 v26, v25
	s_mov_b32 s0, 0xfc2757d1
	v_mad_u64_u32 v[26:27], s[0:1], v12, s0, v[26:27]
	v_mov_b32_e32 v28, v27
	s_mov_b32 s0, 0x4e441529
	v_mad_u64_u32 v[28:29], s[0:1], v12, s0, v[28:29]
	v_mov_b32_e32 v30, v29
	v_mov_b32_e32 v31, v2
	s_mov_b32 s0, 0xa2f9836e
	v_mad_u64_u32 v[30:31], s[0:1], v12, s0, v[30:31]
	v_cndmask_b32_e32 v17, v28, v24, vcc
	v_cndmask_b32_e32 v12, v30, v26, vcc
	v_cndmask_b32_e32 v21, v31, v28, vcc
	v_cndmask_b32_e64 v19, v12, v17, s[34:35]
	v_cndmask_b32_e64 v12, v21, v12, s[34:35]
	v_cndmask_b32_e32 v21, v26, v22, vcc
	v_cndmask_b32_e64 v17, v17, v21, s[34:35]
	v_cndmask_b32_e64 v12, v12, v19, s[36:37]
	v_cndmask_b32_e64 v19, v19, v17, s[36:37]
	v_sub_u32_e32 v23, 32, v11
	v_alignbit_b32 v25, v12, v19, v23
	v_cmp_eq_u32_e64 s[38:39], 0, v11
	v_cndmask_b32_e32 v18, v22, v18, vcc
	s_mov_b32 s0, 0x3fc90fda
	v_cndmask_b32_e64 v11, v25, v12, s[38:39]
	v_cndmask_b32_e32 v12, v24, v20, vcc
	v_cndmask_b32_e64 v20, v21, v12, s[34:35]
	v_cndmask_b32_e64 v17, v17, v20, s[36:37]
	v_alignbit_b32 v21, v19, v17, v23
	v_cndmask_b32_e64 v12, v12, v18, s[34:35]
	v_cndmask_b32_e64 v19, v21, v19, s[38:39]
	v_bfe_u32 v25, v11, 29, 1
	v_cndmask_b32_e64 v12, v20, v12, s[36:37]
	v_alignbit_b32 v21, v11, v19, 30
	v_sub_u32_e32 v26, 0, v25
	v_alignbit_b32 v18, v17, v12, v23
	v_xor_b32_e32 v21, v21, v26
	v_cndmask_b32_e64 v17, v18, v17, s[38:39]
	v_alignbit_b32 v18, v19, v17, 30
	v_ffbh_u32_e32 v19, v21
	v_min_u32_e32 v19, 32, v19
	v_alignbit_b32 v12, v17, v12, 30
	v_xor_b32_e32 v18, v18, v26
	v_sub_u32_e32 v20, 31, v19
	v_xor_b32_e32 v12, v12, v26
	v_alignbit_b32 v21, v21, v18, v20
	v_alignbit_b32 v12, v18, v12, v20
	v_alignbit_b32 v17, v21, v12, 9
	v_ffbh_u32_e32 v18, v17
	v_min_u32_e32 v18, 32, v18
	v_lshrrev_b32_e32 v24, 29, v11
	v_not_b32_e32 v20, v18
	v_alignbit_b32 v12, v17, v12, v20
	v_lshlrev_b32_e32 v17, 31, v24
	v_or_b32_e32 v20, 0x33000000, v17
	v_add_lshl_u32 v18, v18, v19, 23
	v_lshrrev_b32_e32 v12, 9, v12
	v_sub_u32_e32 v18, v20, v18
	v_or_b32_e32 v17, 0.5, v17
	v_lshlrev_b32_e32 v19, 23, v19
	v_or_b32_e32 v12, v18, v12
	v_lshrrev_b32_e32 v18, 9, v21
	v_sub_u32_e32 v17, v17, v19
	v_or_b32_e32 v17, v18, v17
	v_mul_f32_e32 v18, 0x3fc90fda, v17
	v_fma_f32 v19, v17, s0, -v18
	v_fmac_f32_e32 v19, 0x33a22168, v17
	v_fmac_f32_e32 v19, 0x3fc90fda, v12
	v_lshrrev_b32_e32 v11, 30, v11
	v_add_f32_e32 v12, v18, v19
	v_add_u32_e32 v11, v25, v11
